# P4 denominator pass of the state scan (4 workgroups): loop unrolled, loads requested two trips ahead
# baseline (speedup 1.0000x reference)
; __device__ __forceinline__ void phase4(const Args& a, LAS unsigned char* lds, int tid, int wave, int lane, int vcu, int G) {
;     ...
;             if ((u & 63) == 0 && tid < 128) { const int dk = tid;
;                 const float* DN = (const float*)(ws + WS_DN); float* NPREV = (float*)(ws + WS_NPREV); float n = 0.f;
;                 for (int c0 = 0; c0 < 128; c0 += 16) { float dn[16];
; #pragma unroll
;                     for (int x = 0; x < 16; ++x) dn[x] = DN[(size_t)((c0 + x) * 4 + hd) * 128 + dk];
; #pragma unroll
;                     for (int x = 0; x < 16; ++x) { NPREV[(size_t)((c0 + x) * 4 + hd) * 128 + dk] = n; n = n * DEC[c0 + x] + dn[x] * SCL[c0 + x]; } }
;                 a.out[O_NP + hd * 128 + dk] = n;
.LBB0_1007:
	v_add_co_u32_e32 v78, vcc, 0xfeef9000, v2
	s_nop 1
	v_addc_co_u32_e32 v79, vcc, -1, v3, vcc
	global_load_dword v46, v[78:79], off offset:-2048
	global_load_dword v47, v[78:79], off
	v_add_co_u32_e32 v78, vcc, 0xfeefa000, v2
	s_nop 1
	v_addc_co_u32_e32 v79, vcc, -1, v3, vcc
	global_load_dword v48, v[78:79], off offset:-2048
	global_load_dword v49, v[78:79], off
	v_add_co_u32_e32 v78, vcc, 0xfeefb000, v2
	s_nop 1
	v_addc_co_u32_e32 v79, vcc, -1, v3, vcc
	global_load_dword v50, v[78:79], off offset:-2048
	global_load_dword v51, v[78:79], off
	v_add_co_u32_e32 v78, vcc, 0xfeefc000, v2
	s_nop 1
	v_addc_co_u32_e32 v79, vcc, -1, v3, vcc
	global_load_dword v52, v[78:79], off offset:-2048
	global_load_dword v53, v[78:79], off
	v_add_co_u32_e32 v78, vcc, 0xfeefd000, v2
	s_nop 1
	v_addc_co_u32_e32 v79, vcc, -1, v3, vcc
	global_load_dword v54, v[78:79], off offset:-2048
	global_load_dword v55, v[78:79], off
	v_add_co_u32_e32 v78, vcc, 0xfeefe000, v2
	s_nop 1
	v_addc_co_u32_e32 v79, vcc, -1, v3, vcc
	global_load_dword v56, v[78:79], off offset:-2048
	global_load_dword v57, v[78:79], off
	v_add_co_u32_e32 v78, vcc, 0xfeeff000, v2
	s_nop 1
	v_addc_co_u32_e32 v79, vcc, -1, v3, vcc
	global_load_dword v58, v[78:79], off offset:-2048
	global_load_dword v59, v[78:79], off
	v_add_co_u32_e32 v78, vcc, 0xfef00000, v2
	s_nop 1
	v_addc_co_u32_e32 v79, vcc, -1, v3, vcc
	global_load_dword v60, v[78:79], off offset:-2048
	global_load_dword v61, v[78:79], off
	v_add_co_u32_e32 v78, vcc, 0xfef01000, v2
	s_nop 1
	v_addc_co_u32_e32 v79, vcc, -1, v3, vcc
	global_load_dword v62, v[78:79], off offset:-2048
	global_load_dword v63, v[78:79], off
	v_add_co_u32_e32 v78, vcc, 0xfef02000, v2
	s_nop 1
	v_addc_co_u32_e32 v79, vcc, -1, v3, vcc
	global_load_dword v64, v[78:79], off offset:-2048
	global_load_dword v65, v[78:79], off
	v_add_co_u32_e32 v78, vcc, 0xfef03000, v2
	s_nop 1
	v_addc_co_u32_e32 v79, vcc, -1, v3, vcc
	global_load_dword v66, v[78:79], off offset:-2048
	global_load_dword v67, v[78:79], off
	v_add_co_u32_e32 v78, vcc, 0xfef04000, v2
	s_nop 1
	v_addc_co_u32_e32 v79, vcc, -1, v3, vcc
	global_load_dword v68, v[78:79], off offset:-2048
	global_load_dword v69, v[78:79], off
	v_add_co_u32_e32 v78, vcc, 0xfef05000, v2
	s_nop 1
	v_addc_co_u32_e32 v79, vcc, -1, v3, vcc
	global_load_dword v70, v[78:79], off offset:-2048
	global_load_dword v71, v[78:79], off
	v_add_co_u32_e32 v78, vcc, 0xfef06000, v2
	s_nop 1
	v_addc_co_u32_e32 v79, vcc, -1, v3, vcc
	global_load_dword v72, v[78:79], off offset:-2048
	global_load_dword v73, v[78:79], off
	v_add_co_u32_e32 v78, vcc, 0xfef07000, v2
	s_nop 1
	v_addc_co_u32_e32 v79, vcc, -1, v3, vcc
	global_load_dword v74, v[78:79], off offset:-2048
	global_load_dword v75, v[78:79], off
	v_add_co_u32_e32 v78, vcc, 0xfef08000, v2
	s_nop 1
	v_addc_co_u32_e32 v79, vcc, -1, v3, vcc
	global_load_dword v76, v[78:79], off offset:-2048
	global_load_dword v77, v[78:79], off
	s_waitcnt vmcnt(16)
	v_mov_b32_e32 v5, v46
	v_mov_b32_e32 v21, v47
	v_mov_b32_e32 v32, v48
	v_mov_b32_e32 v33, v49
	v_mov_b32_e32 v20, v50
	v_mov_b32_e32 v19, v51
	v_mov_b32_e32 v17, v52
	v_mov_b32_e32 v16, v53
	v_mov_b32_e32 v15, v54
	v_mov_b32_e32 v14, v55
	v_mov_b32_e32 v13, v56
	v_mov_b32_e32 v12, v57
	v_mov_b32_e32 v11, v58
	v_mov_b32_e32 v10, v59
	v_mov_b32_e32 v9, v60
	v_mov_b32_e32 v8, v61
	v_add_co_u32_e32 v78, vcc, 0xfef09000, v2
	s_nop 1
	v_addc_co_u32_e32 v79, vcc, -1, v3, vcc
	global_load_dword v46, v[78:79], off offset:-2048
	global_load_dword v47, v[78:79], off
	v_add_co_u32_e32 v78, vcc, 0xfef0a000, v2
	s_nop 1
	v_addc_co_u32_e32 v79, vcc, -1, v3, vcc
	global_load_dword v48, v[78:79], off offset:-2048
	global_load_dword v49, v[78:79], off
	v_add_co_u32_e32 v78, vcc, 0xfef0b000, v2
	s_nop 1
	v_addc_co_u32_e32 v79, vcc, -1, v3, vcc
	global_load_dword v50, v[78:79], off offset:-2048
	global_load_dword v51, v[78:79], off
	v_add_co_u32_e32 v78, vcc, 0xfef0c000, v2
	s_nop 1
	v_addc_co_u32_e32 v79, vcc, -1, v3, vcc
	global_load_dword v52, v[78:79], off offset:-2048
	global_load_dword v53, v[78:79], off
	v_add_co_u32_e32 v78, vcc, 0xfef0d000, v2
	s_nop 1
	v_addc_co_u32_e32 v79, vcc, -1, v3, vcc
	global_load_dword v54, v[78:79], off offset:-2048
	global_load_dword v55, v[78:79], off
	v_add_co_u32_e32 v78, vcc, 0xfef0e000, v2
	s_nop 1
	v_addc_co_u32_e32 v79, vcc, -1, v3, vcc
	global_load_dword v56, v[78:79], off offset:-2048
	global_load_dword v57, v[78:79], off
	v_add_co_u32_e32 v78, vcc, 0xfef0f000, v2
	s_nop 1
	v_addc_co_u32_e32 v79, vcc, -1, v3, vcc
	global_load_dword v58, v[78:79], off offset:-2048
	global_load_dword v59, v[78:79], off
	v_add_co_u32_e32 v78, vcc, 0xfef10000, v2
	s_nop 1
	v_addc_co_u32_e32 v79, vcc, -1, v3, vcc
	global_load_dword v60, v[78:79], off offset:-2048
	global_load_dword v61, v[78:79], off
	v_mov_b32_e32 v18, s4
	s_nop 0
	s_movk_i32 s5, 0xa000
	s_nop 0
	s_add_i32 s1, s1, 16
	s_nop 0
	s_mov_b64 s[6:7], 0x8000
	s_nop 0
	s_add_i32 s4, s4, 64
	s_nop 0
	s_cmpk_gt_u32 s1, 0x6f
	s_nop 0
	s_nop 1
	s_nop 1
	v_add_co_u32_e32 v6, vcc, 0xffff9000, v2
	s_nop 1
	v_addc_co_u32_e32 v7, vcc, -1, v3, vcc
	global_store_dword v[6:7], v4, off offset:-2048
	ds_read_b128 v[22:25], v18
	ds_read_b128 v[26:29], v18 offset:512
	s_waitcnt lgkmcnt(1)
	v_mov_b32_e32 v30, v22
	s_waitcnt lgkmcnt(0)
; __device__ __forceinline__ void phase4(const Args& a, LAS unsigned char* lds, int tid, int wave, int lane, int vcu, int G) {
;     ...
;                 for (int c0 = 0; c0 < 128; c0 += 16) { float dn[16];
; #pragma unroll
;                     for (int x = 0; x < 16; ++x) dn[x] = DN[(size_t)((c0 + x) * 4 + hd) * 128 + dk];
; #pragma unroll
;                     for (int x = 0; x < 16; ++x) { NPREV[(size_t)((c0 + x) * 4 + hd) * 128 + dk] = n; n = n * DEC[c0 + x] + dn[x] * SCL[c0 + x]; } }
	v_mov_b32_e32 v31, v26
	v_mul_f32_e32 v22, v5, v26
	v_pk_fma_f32 v[4:5], v[4:5], v[30:31], v[22:23] op_sel_hi:[1,1,0]
	global_store_dword v[6:7], v4, off
	v_mov_b32_e32 v5, v21
	v_mov_b32_e32 v26, v23
	v_mul_f32_e32 v6, v21, v27
	v_pk_fma_f32 v[4:5], v[4:5], v[26:27], v[6:7] op_sel_hi:[1,1,0]
	v_add_co_u32_e32 v6, vcc, s5, v2
	v_mov_b32_e32 v5, v32
	v_addc_co_u32_e32 v7, vcc, -1, v3, vcc
	global_store_dword v[6:7], v4, off offset:-2048
	v_mov_b32_e32 v6, v24
	v_mov_b32_e32 v7, v28
	v_mul_f32_e32 v22, v32, v28
	s_movk_i32 s5, 0xb000
	v_pk_fma_f32 v[6:7], v[4:5], v[6:7], v[22:23] op_sel_hi:[1,1,0]
	v_add_co_u32_e32 v4, vcc, s5, v2
	v_mov_b32_e32 v7, v33
	v_addc_co_u32_e32 v5, vcc, -1, v3, vcc
	v_mov_b32_e32 v28, v25
	v_mul_f32_e32 v22, v33, v29
	global_store_dword v[4:5], v6, off offset:-4096
	v_pk_fma_f32 v[6:7], v[6:7], v[28:29], v[22:23] op_sel_hi:[1,1,0]
	global_store_dword v[4:5], v6, off offset:-2048
	ds_read_b128 v[22:25], v18 offset:16
	ds_read_b128 v[26:29], v18 offset:528
	v_mov_b32_e32 v7, v20
	s_movk_i32 s5, 0xc000
	s_waitcnt lgkmcnt(1)
	v_mov_b32_e32 v30, v22
	s_waitcnt lgkmcnt(0)
	v_mov_b32_e32 v31, v26
	v_mul_f32_e32 v20, v20, v26
	v_pk_fma_f32 v[6:7], v[6:7], v[30:31], v[20:21] op_sel_hi:[1,1,0]
	global_store_dword v[4:5], v6, off
	v_mov_b32_e32 v7, v19
	v_mov_b32_e32 v26, v23
	v_mul_f32_e32 v4, v19, v27
	v_pk_fma_f32 v[4:5], v[6:7], v[26:27], v[4:5] op_sel_hi:[1,1,0]
	v_add_co_u32_e32 v6, vcc, s5, v2
	v_mov_b32_e32 v5, v17
	v_addc_co_u32_e32 v7, vcc, -1, v3, vcc
	global_store_dword v[6:7], v4, off offset:-2048
	v_mov_b32_e32 v6, v24
	v_mov_b32_e32 v7, v28
	v_mul_f32_e32 v20, v17, v28
	v_pk_fma_f32 v[4:5], v[4:5], v[6:7], v[20:21] op_sel_hi:[1,1,0]
	s_movk_i32 s5, 0xd000
	v_add_co_u32_e32 v26, vcc, s5, v2
	v_mov_b32_e32 v5, v16
	v_mov_b32_e32 v28, v25
	v_mul_f32_e32 v6, v16, v29
	v_addc_co_u32_e32 v27, vcc, -1, v3, vcc
	v_pk_fma_f32 v[16:17], v[4:5], v[28:29], v[6:7] op_sel_hi:[1,1,0]
	global_store_dword v[26:27], v4, off offset:-4096
	global_store_dword v[26:27], v16, off offset:-2048
	ds_read_b128 v[4:7], v18 offset:32
	ds_read_b128 v[20:23], v18 offset:544
	v_mov_b32_e32 v17, v15
	s_movk_i32 s5, 0xe000
	s_waitcnt lgkmcnt(1)
	v_mov_b32_e32 v24, v4
	s_waitcnt lgkmcnt(0)
	v_mov_b32_e32 v25, v20
	v_mul_f32_e32 v4, v15, v20
	v_pk_fma_f32 v[16:17], v[16:17], v[24:25], v[4:5] op_sel_hi:[1,1,0]
	v_mov_b32_e32 v20, v5
	v_mov_b32_e32 v17, v14
	v_mul_f32_e32 v4, v14, v21
	v_pk_fma_f32 v[4:5], v[16:17], v[20:21], v[4:5] op_sel_hi:[1,1,0]
	v_add_co_u32_e32 v14, vcc, s5, v2
	global_store_dword v[26:27], v16, off
	s_nop 0
	v_addc_co_u32_e32 v15, vcc, -1, v3, vcc
	v_mov_b32_e32 v5, v13
	v_mov_b32_e32 v16, v6
	v_mov_b32_e32 v17, v22
	v_mul_f32_e32 v6, v13, v22
	global_store_dword v[14:15], v4, off offset:-2048
	v_pk_fma_f32 v[4:5], v[4:5], v[16:17], v[6:7] op_sel_hi:[1,1,0]
	v_mov_b32_e32 v22, v7
	v_mov_b32_e32 v5, v12
	v_mul_f32_e32 v6, v12, v23
	s_movk_i32 s5, 0xf000
	global_store_dword v[14:15], v4, off
	v_pk_fma_f32 v[16:17], v[4:5], v[22:23], v[6:7] op_sel_hi:[1,1,0]
	v_add_co_u32_e32 v4, vcc, s5, v2
	v_mov_b32_e32 v17, v11
	v_addc_co_u32_e32 v5, vcc, -1, v3, vcc
	global_store_dword v[4:5], v16, off offset:-2048
	ds_read_b128 v[4:7], v18 offset:48
	ds_read_b128 v[12:15], v18 offset:560
	s_waitcnt lgkmcnt(1)
	v_mov_b32_e32 v18, v4
	s_waitcnt lgkmcnt(0)
	v_mov_b32_e32 v19, v12
	v_mul_f32_e32 v4, v11, v12
	v_pk_fma_f32 v[16:17], v[16:17], v[18:19], v[4:5] op_sel_hi:[1,1,0]
	v_mov_b32_e32 v12, v5
	v_mov_b32_e32 v17, v10
	v_mul_f32_e32 v4, v10, v13
	v_pk_fma_f32 v[4:5], v[16:17], v[12:13], v[4:5] op_sel_hi:[1,1,0]
	v_mov_b32_e32 v10, v6
	v_mov_b32_e32 v5, v9
	v_mov_b32_e32 v11, v14
	global_store_dword v[2:3], v4, off offset:-2048
	v_pk_mul_f32 v[4:5], v[4:5], v[10:11]
	global_store_dword v[2:3], v16, off offset:-4096
	v_add_f32_e32 v5, v4, v5
	v_mul_f32_e32 v4, v8, v15
	global_store_dword v[2:3], v5, off
	v_fmac_f32_e32 v4, v5, v7
	v_lshl_add_u64 v[2:3], v[2:3], 0, s[6:7]
	s_waitcnt vmcnt(32)
	v_mov_b32_e32 v5, v62
	v_mov_b32_e32 v21, v63
	v_mov_b32_e32 v32, v64
	v_mov_b32_e32 v33, v65
	v_mov_b32_e32 v20, v66
	v_mov_b32_e32 v19, v67
	v_mov_b32_e32 v17, v68
	v_mov_b32_e32 v16, v69
	v_mov_b32_e32 v15, v70
	v_mov_b32_e32 v14, v71
	v_mov_b32_e32 v13, v72
	v_mov_b32_e32 v12, v73
	v_mov_b32_e32 v11, v74
	v_mov_b32_e32 v10, v75
	v_mov_b32_e32 v9, v76
	v_mov_b32_e32 v8, v77
	v_add_co_u32_e32 v78, vcc, 0xfef09000, v2
	s_nop 1
	v_addc_co_u32_e32 v79, vcc, -1, v3, vcc
	global_load_dword v62, v[78:79], off offset:-2048
	global_load_dword v63, v[78:79], off
	v_add_co_u32_e32 v78, vcc, 0xfef0a000, v2
	s_nop 1
	v_addc_co_u32_e32 v79, vcc, -1, v3, vcc
	global_load_dword v64, v[78:79], off offset:-2048
	global_load_dword v65, v[78:79], off
	v_add_co_u32_e32 v78, vcc, 0xfef0b000, v2
	s_nop 1
	v_addc_co_u32_e32 v79, vcc, -1, v3, vcc
	global_load_dword v66, v[78:79], off offset:-2048
	global_load_dword v67, v[78:79], off
	v_add_co_u32_e32 v78, vcc, 0xfef0c000, v2
	s_nop 1
	v_addc_co_u32_e32 v79, vcc, -1, v3, vcc
	global_load_dword v68, v[78:79], off offset:-2048
	global_load_dword v69, v[78:79], off
	v_add_co_u32_e32 v78, vcc, 0xfef0d000, v2
	s_nop 1
	v_addc_co_u32_e32 v79, vcc, -1, v3, vcc
	global_load_dword v70, v[78:79], off offset:-2048
	global_load_dword v71, v[78:79], off
	v_add_co_u32_e32 v78, vcc, 0xfef0e000, v2
	s_nop 1
	v_addc_co_u32_e32 v79, vcc, -1, v3, vcc
	global_load_dword v72, v[78:79], off offset:-2048
	global_load_dword v73, v[78:79], off
	v_add_co_u32_e32 v78, vcc, 0xfef0f000, v2
	s_nop 1
	v_addc_co_u32_e32 v79, vcc, -1, v3, vcc
	global_load_dword v74, v[78:79], off offset:-2048
	global_load_dword v75, v[78:79], off
	v_add_co_u32_e32 v78, vcc, 0xfef10000, v2
	s_nop 1
	v_addc_co_u32_e32 v79, vcc, -1, v3, vcc
	global_load_dword v76, v[78:79], off offset:-2048
	global_load_dword v77, v[78:79], off
	v_mov_b32_e32 v18, s4
	s_nop 0
	s_movk_i32 s5, 0xa000
	s_nop 0
	s_add_i32 s1, s1, 16
	s_nop 0
	s_mov_b64 s[6:7], 0x8000
	s_nop 0
	s_add_i32 s4, s4, 64
	s_nop 0
	s_cmpk_gt_u32 s1, 0x6f
	s_nop 0
	s_nop 1
	s_nop 1
	v_add_co_u32_e32 v6, vcc, 0xffff9000, v2
	s_nop 1
	v_addc_co_u32_e32 v7, vcc, -1, v3, vcc
	global_store_dword v[6:7], v4, off offset:-2048
	ds_read_b128 v[22:25], v18
	ds_read_b128 v[26:29], v18 offset:512
	s_waitcnt lgkmcnt(1)
; __device__ __forceinline__ void phase4(const Args& a, LAS unsigned char* lds, int tid, int wave, int lane, int vcu, int G) {
;     ...
;                 for (int c0 = 0; c0 < 128; c0 += 16) { float dn[16];
; #pragma unroll
;                     for (int x = 0; x < 16; ++x) dn[x] = DN[(size_t)((c0 + x) * 4 + hd) * 128 + dk];
; #pragma unroll
;                     for (int x = 0; x < 16; ++x) { NPREV[(size_t)((c0 + x) * 4 + hd) * 128 + dk] = n; n = n * DEC[c0 + x] + dn[x] * SCL[c0 + x]; } }
	v_mov_b32_e32 v30, v22
	s_waitcnt lgkmcnt(0)
	v_mov_b32_e32 v31, v26
	v_mul_f32_e32 v22, v5, v26
	v_pk_fma_f32 v[4:5], v[4:5], v[30:31], v[22:23] op_sel_hi:[1,1,0]
	global_store_dword v[6:7], v4, off
	v_mov_b32_e32 v5, v21
	v_mov_b32_e32 v26, v23
	v_mul_f32_e32 v6, v21, v27
	v_pk_fma_f32 v[4:5], v[4:5], v[26:27], v[6:7] op_sel_hi:[1,1,0]
	v_add_co_u32_e32 v6, vcc, s5, v2
	v_mov_b32_e32 v5, v32
	v_addc_co_u32_e32 v7, vcc, -1, v3, vcc
	global_store_dword v[6:7], v4, off offset:-2048
	v_mov_b32_e32 v6, v24
	v_mov_b32_e32 v7, v28
	v_mul_f32_e32 v22, v32, v28
	s_movk_i32 s5, 0xb000
	v_pk_fma_f32 v[6:7], v[4:5], v[6:7], v[22:23] op_sel_hi:[1,1,0]
	v_add_co_u32_e32 v4, vcc, s5, v2
	v_mov_b32_e32 v7, v33
	v_addc_co_u32_e32 v5, vcc, -1, v3, vcc
	v_mov_b32_e32 v28, v25
	v_mul_f32_e32 v22, v33, v29
	global_store_dword v[4:5], v6, off offset:-4096
	v_pk_fma_f32 v[6:7], v[6:7], v[28:29], v[22:23] op_sel_hi:[1,1,0]
	global_store_dword v[4:5], v6, off offset:-2048
	ds_read_b128 v[22:25], v18 offset:16
	ds_read_b128 v[26:29], v18 offset:528
	v_mov_b32_e32 v7, v20
	s_movk_i32 s5, 0xc000
	s_waitcnt lgkmcnt(1)
	v_mov_b32_e32 v30, v22
	s_waitcnt lgkmcnt(0)
	v_mov_b32_e32 v31, v26
	v_mul_f32_e32 v20, v20, v26
	v_pk_fma_f32 v[6:7], v[6:7], v[30:31], v[20:21] op_sel_hi:[1,1,0]
	global_store_dword v[4:5], v6, off
	v_mov_b32_e32 v7, v19
	v_mov_b32_e32 v26, v23
	v_mul_f32_e32 v4, v19, v27
	v_pk_fma_f32 v[4:5], v[6:7], v[26:27], v[4:5] op_sel_hi:[1,1,0]
	v_add_co_u32_e32 v6, vcc, s5, v2
	v_mov_b32_e32 v5, v17
	v_addc_co_u32_e32 v7, vcc, -1, v3, vcc
	global_store_dword v[6:7], v4, off offset:-2048
	v_mov_b32_e32 v6, v24
	v_mov_b32_e32 v7, v28
	v_mul_f32_e32 v20, v17, v28
	v_pk_fma_f32 v[4:5], v[4:5], v[6:7], v[20:21] op_sel_hi:[1,1,0]
	s_movk_i32 s5, 0xd000
	v_add_co_u32_e32 v26, vcc, s5, v2
	v_mov_b32_e32 v5, v16
	v_mov_b32_e32 v28, v25
	v_mul_f32_e32 v6, v16, v29
	v_addc_co_u32_e32 v27, vcc, -1, v3, vcc
	v_pk_fma_f32 v[16:17], v[4:5], v[28:29], v[6:7] op_sel_hi:[1,1,0]
	global_store_dword v[26:27], v4, off offset:-4096
	global_store_dword v[26:27], v16, off offset:-2048
	ds_read_b128 v[4:7], v18 offset:32
	ds_read_b128 v[20:23], v18 offset:544
	v_mov_b32_e32 v17, v15
	s_movk_i32 s5, 0xe000
	s_waitcnt lgkmcnt(1)
	v_mov_b32_e32 v24, v4
	s_waitcnt lgkmcnt(0)
	v_mov_b32_e32 v25, v20
	v_mul_f32_e32 v4, v15, v20
	v_pk_fma_f32 v[16:17], v[16:17], v[24:25], v[4:5] op_sel_hi:[1,1,0]
	v_mov_b32_e32 v20, v5
	v_mov_b32_e32 v17, v14
	v_mul_f32_e32 v4, v14, v21
	v_pk_fma_f32 v[4:5], v[16:17], v[20:21], v[4:5] op_sel_hi:[1,1,0]
	v_add_co_u32_e32 v14, vcc, s5, v2
	global_store_dword v[26:27], v16, off
	s_nop 0
	v_addc_co_u32_e32 v15, vcc, -1, v3, vcc
	v_mov_b32_e32 v5, v13
	v_mov_b32_e32 v16, v6
	v_mov_b32_e32 v17, v22
	v_mul_f32_e32 v6, v13, v22
	global_store_dword v[14:15], v4, off offset:-2048
	v_pk_fma_f32 v[4:5], v[4:5], v[16:17], v[6:7] op_sel_hi:[1,1,0]
	v_mov_b32_e32 v22, v7
	v_mov_b32_e32 v5, v12
	v_mul_f32_e32 v6, v12, v23
	s_movk_i32 s5, 0xf000
	global_store_dword v[14:15], v4, off
	v_pk_fma_f32 v[16:17], v[4:5], v[22:23], v[6:7] op_sel_hi:[1,1,0]
	v_add_co_u32_e32 v4, vcc, s5, v2
	v_mov_b32_e32 v17, v11
	v_addc_co_u32_e32 v5, vcc, -1, v3, vcc
	global_store_dword v[4:5], v16, off offset:-2048
	ds_read_b128 v[4:7], v18 offset:48
	ds_read_b128 v[12:15], v18 offset:560
	s_waitcnt lgkmcnt(1)
	v_mov_b32_e32 v18, v4
	s_waitcnt lgkmcnt(0)
	v_mov_b32_e32 v19, v12
	v_mul_f32_e32 v4, v11, v12
	v_pk_fma_f32 v[16:17], v[16:17], v[18:19], v[4:5] op_sel_hi:[1,1,0]
	v_mov_b32_e32 v12, v5
	v_mov_b32_e32 v17, v10
	v_mul_f32_e32 v4, v10, v13
	v_pk_fma_f32 v[4:5], v[16:17], v[12:13], v[4:5] op_sel_hi:[1,1,0]
	v_mov_b32_e32 v10, v6
	v_mov_b32_e32 v5, v9
	v_mov_b32_e32 v11, v14
	global_store_dword v[2:3], v4, off offset:-2048
	v_pk_mul_f32 v[4:5], v[4:5], v[10:11]
	global_store_dword v[2:3], v16, off offset:-4096
	v_add_f32_e32 v5, v4, v5
	v_mul_f32_e32 v4, v8, v15
	global_store_dword v[2:3], v5, off
	v_fmac_f32_e32 v4, v5, v7
	v_lshl_add_u64 v[2:3], v[2:3], 0, s[6:7]
	s_waitcnt vmcnt(48)
	v_mov_b32_e32 v5, v46
	v_mov_b32_e32 v21, v47
	v_mov_b32_e32 v32, v48
	v_mov_b32_e32 v33, v49
	v_mov_b32_e32 v20, v50
	v_mov_b32_e32 v19, v51
	v_mov_b32_e32 v17, v52
	v_mov_b32_e32 v16, v53
	v_mov_b32_e32 v15, v54
	v_mov_b32_e32 v14, v55
	v_mov_b32_e32 v13, v56
	v_mov_b32_e32 v12, v57
	v_mov_b32_e32 v11, v58
	v_mov_b32_e32 v10, v59
	v_mov_b32_e32 v9, v60
	v_mov_b32_e32 v8, v61
	v_add_co_u32_e32 v78, vcc, 0xfef09000, v2
	s_nop 1
	v_addc_co_u32_e32 v79, vcc, -1, v3, vcc
	global_load_dword v46, v[78:79], off offset:-2048
	global_load_dword v47, v[78:79], off
	v_add_co_u32_e32 v78, vcc, 0xfef0a000, v2
	s_nop 1
	v_addc_co_u32_e32 v79, vcc, -1, v3, vcc
	global_load_dword v48, v[78:79], off offset:-2048
	global_load_dword v49, v[78:79], off
	v_add_co_u32_e32 v78, vcc, 0xfef0b000, v2
	s_nop 1
	v_addc_co_u32_e32 v79, vcc, -1, v3, vcc
	global_load_dword v50, v[78:79], off offset:-2048
	global_load_dword v51, v[78:79], off
	v_add_co_u32_e32 v78, vcc, 0xfef0c000, v2
	s_nop 1
	v_addc_co_u32_e32 v79, vcc, -1, v3, vcc
	global_load_dword v52, v[78:79], off offset:-2048
	global_load_dword v53, v[78:79], off
	v_add_co_u32_e32 v78, vcc, 0xfef0d000, v2
	s_nop 1
	v_addc_co_u32_e32 v79, vcc, -1, v3, vcc
	global_load_dword v54, v[78:79], off offset:-2048
	global_load_dword v55, v[78:79], off
	v_add_co_u32_e32 v78, vcc, 0xfef0e000, v2
	s_nop 1
	v_addc_co_u32_e32 v79, vcc, -1, v3, vcc
	global_load_dword v56, v[78:79], off offset:-2048
	global_load_dword v57, v[78:79], off
	v_add_co_u32_e32 v78, vcc, 0xfef0f000, v2
	s_nop 1
	v_addc_co_u32_e32 v79, vcc, -1, v3, vcc
	global_load_dword v58, v[78:79], off offset:-2048
	global_load_dword v59, v[78:79], off
	v_add_co_u32_e32 v78, vcc, 0xfef10000, v2
	s_nop 1
	v_addc_co_u32_e32 v79, vcc, -1, v3, vcc
	global_load_dword v60, v[78:79], off offset:-2048
	global_load_dword v61, v[78:79], off
	v_mov_b32_e32 v18, s4
	s_nop 0
	s_movk_i32 s5, 0xa000
	s_nop 0
	s_add_i32 s1, s1, 16
	s_nop 0
	s_mov_b64 s[6:7], 0x8000
	s_nop 0
	s_add_i32 s4, s4, 64
	s_nop 0
	s_cmpk_gt_u32 s1, 0x6f
	s_nop 0
	s_nop 1
	s_nop 1
	v_add_co_u32_e32 v6, vcc, 0xffff9000, v2
	s_nop 1
	v_addc_co_u32_e32 v7, vcc, -1, v3, vcc
	global_store_dword v[6:7], v4, off offset:-2048
	ds_read_b128 v[22:25], v18
	ds_read_b128 v[26:29], v18 offset:512
	s_waitcnt lgkmcnt(1)
; __device__ __forceinline__ void phase4(const Args& a, LAS unsigned char* lds, int tid, int wave, int lane, int vcu, int G) {
;     ...
;                 for (int c0 = 0; c0 < 128; c0 += 16) { float dn[16];
; #pragma unroll
;                     for (int x = 0; x < 16; ++x) dn[x] = DN[(size_t)((c0 + x) * 4 + hd) * 128 + dk];
; #pragma unroll
;                     for (int x = 0; x < 16; ++x) { NPREV[(size_t)((c0 + x) * 4 + hd) * 128 + dk] = n; n = n * DEC[c0 + x] + dn[x] * SCL[c0 + x]; } }
	v_mov_b32_e32 v30, v22
	s_waitcnt lgkmcnt(0)
	v_mov_b32_e32 v31, v26
	v_mul_f32_e32 v22, v5, v26
	v_pk_fma_f32 v[4:5], v[4:5], v[30:31], v[22:23] op_sel_hi:[1,1,0]
	global_store_dword v[6:7], v4, off
	v_mov_b32_e32 v5, v21
	v_mov_b32_e32 v26, v23
	v_mul_f32_e32 v6, v21, v27
	v_pk_fma_f32 v[4:5], v[4:5], v[26:27], v[6:7] op_sel_hi:[1,1,0]
	v_add_co_u32_e32 v6, vcc, s5, v2
	v_mov_b32_e32 v5, v32
	v_addc_co_u32_e32 v7, vcc, -1, v3, vcc
	global_store_dword v[6:7], v4, off offset:-2048
	v_mov_b32_e32 v6, v24
	v_mov_b32_e32 v7, v28
	v_mul_f32_e32 v22, v32, v28
	s_movk_i32 s5, 0xb000
	v_pk_fma_f32 v[6:7], v[4:5], v[6:7], v[22:23] op_sel_hi:[1,1,0]
	v_add_co_u32_e32 v4, vcc, s5, v2
	v_mov_b32_e32 v7, v33
	v_addc_co_u32_e32 v5, vcc, -1, v3, vcc
	v_mov_b32_e32 v28, v25
	v_mul_f32_e32 v22, v33, v29
	global_store_dword v[4:5], v6, off offset:-4096
	v_pk_fma_f32 v[6:7], v[6:7], v[28:29], v[22:23] op_sel_hi:[1,1,0]
	global_store_dword v[4:5], v6, off offset:-2048
	ds_read_b128 v[22:25], v18 offset:16
	ds_read_b128 v[26:29], v18 offset:528
	v_mov_b32_e32 v7, v20
	s_movk_i32 s5, 0xc000
	s_waitcnt lgkmcnt(1)
	v_mov_b32_e32 v30, v22
	s_waitcnt lgkmcnt(0)
	v_mov_b32_e32 v31, v26
	v_mul_f32_e32 v20, v20, v26
	v_pk_fma_f32 v[6:7], v[6:7], v[30:31], v[20:21] op_sel_hi:[1,1,0]
	global_store_dword v[4:5], v6, off
	v_mov_b32_e32 v7, v19
	v_mov_b32_e32 v26, v23
	v_mul_f32_e32 v4, v19, v27
	v_pk_fma_f32 v[4:5], v[6:7], v[26:27], v[4:5] op_sel_hi:[1,1,0]
	v_add_co_u32_e32 v6, vcc, s5, v2
	v_mov_b32_e32 v5, v17
	v_addc_co_u32_e32 v7, vcc, -1, v3, vcc
	global_store_dword v[6:7], v4, off offset:-2048
	v_mov_b32_e32 v6, v24
	v_mov_b32_e32 v7, v28
	v_mul_f32_e32 v20, v17, v28
	v_pk_fma_f32 v[4:5], v[4:5], v[6:7], v[20:21] op_sel_hi:[1,1,0]
	s_movk_i32 s5, 0xd000
	v_add_co_u32_e32 v26, vcc, s5, v2
	v_mov_b32_e32 v5, v16
	v_mov_b32_e32 v28, v25
	v_mul_f32_e32 v6, v16, v29
	v_addc_co_u32_e32 v27, vcc, -1, v3, vcc
	v_pk_fma_f32 v[16:17], v[4:5], v[28:29], v[6:7] op_sel_hi:[1,1,0]
	global_store_dword v[26:27], v4, off offset:-4096
	global_store_dword v[26:27], v16, off offset:-2048
	ds_read_b128 v[4:7], v18 offset:32
	ds_read_b128 v[20:23], v18 offset:544
	v_mov_b32_e32 v17, v15
	s_movk_i32 s5, 0xe000
	s_waitcnt lgkmcnt(1)
	v_mov_b32_e32 v24, v4
	s_waitcnt lgkmcnt(0)
	v_mov_b32_e32 v25, v20
	v_mul_f32_e32 v4, v15, v20
	v_pk_fma_f32 v[16:17], v[16:17], v[24:25], v[4:5] op_sel_hi:[1,1,0]
	v_mov_b32_e32 v20, v5
	v_mov_b32_e32 v17, v14
	v_mul_f32_e32 v4, v14, v21
	v_pk_fma_f32 v[4:5], v[16:17], v[20:21], v[4:5] op_sel_hi:[1,1,0]
	v_add_co_u32_e32 v14, vcc, s5, v2
	global_store_dword v[26:27], v16, off
	s_nop 0
	v_addc_co_u32_e32 v15, vcc, -1, v3, vcc
	v_mov_b32_e32 v5, v13
	v_mov_b32_e32 v16, v6
	v_mov_b32_e32 v17, v22
	v_mul_f32_e32 v6, v13, v22
	global_store_dword v[14:15], v4, off offset:-2048
	v_pk_fma_f32 v[4:5], v[4:5], v[16:17], v[6:7] op_sel_hi:[1,1,0]
	v_mov_b32_e32 v22, v7
	v_mov_b32_e32 v5, v12
	v_mul_f32_e32 v6, v12, v23
	s_movk_i32 s5, 0xf000
	global_store_dword v[14:15], v4, off
	v_pk_fma_f32 v[16:17], v[4:5], v[22:23], v[6:7] op_sel_hi:[1,1,0]
	v_add_co_u32_e32 v4, vcc, s5, v2
	v_mov_b32_e32 v17, v11
	v_addc_co_u32_e32 v5, vcc, -1, v3, vcc
	global_store_dword v[4:5], v16, off offset:-2048
	ds_read_b128 v[4:7], v18 offset:48
	ds_read_b128 v[12:15], v18 offset:560
	s_waitcnt lgkmcnt(1)
	v_mov_b32_e32 v18, v4
	s_waitcnt lgkmcnt(0)
	v_mov_b32_e32 v19, v12
	v_mul_f32_e32 v4, v11, v12
	v_pk_fma_f32 v[16:17], v[16:17], v[18:19], v[4:5] op_sel_hi:[1,1,0]
	v_mov_b32_e32 v12, v5
	v_mov_b32_e32 v17, v10
	v_mul_f32_e32 v4, v10, v13
	v_pk_fma_f32 v[4:5], v[16:17], v[12:13], v[4:5] op_sel_hi:[1,1,0]
	v_mov_b32_e32 v10, v6
	v_mov_b32_e32 v5, v9
	v_mov_b32_e32 v11, v14
	global_store_dword v[2:3], v4, off offset:-2048
	v_pk_mul_f32 v[4:5], v[4:5], v[10:11]
	global_store_dword v[2:3], v16, off offset:-4096
	v_add_f32_e32 v5, v4, v5
	v_mul_f32_e32 v4, v8, v15
	global_store_dword v[2:3], v5, off
	v_fmac_f32_e32 v4, v5, v7
	v_lshl_add_u64 v[2:3], v[2:3], 0, s[6:7]
	s_waitcnt vmcnt(48)
	v_mov_b32_e32 v5, v62
	v_mov_b32_e32 v21, v63
	v_mov_b32_e32 v32, v64
	v_mov_b32_e32 v33, v65
	v_mov_b32_e32 v20, v66
	v_mov_b32_e32 v19, v67
	v_mov_b32_e32 v17, v68
	v_mov_b32_e32 v16, v69
	v_mov_b32_e32 v15, v70
	v_mov_b32_e32 v14, v71
	v_mov_b32_e32 v13, v72
	v_mov_b32_e32 v12, v73
	v_mov_b32_e32 v11, v74
	v_mov_b32_e32 v10, v75
	v_mov_b32_e32 v9, v76
	v_mov_b32_e32 v8, v77
	v_add_co_u32_e32 v78, vcc, 0xfef09000, v2
	s_nop 1
	v_addc_co_u32_e32 v79, vcc, -1, v3, vcc
	global_load_dword v62, v[78:79], off offset:-2048
	global_load_dword v63, v[78:79], off
	v_add_co_u32_e32 v78, vcc, 0xfef0a000, v2
	s_nop 1
	v_addc_co_u32_e32 v79, vcc, -1, v3, vcc
	global_load_dword v64, v[78:79], off offset:-2048
	global_load_dword v65, v[78:79], off
	v_add_co_u32_e32 v78, vcc, 0xfef0b000, v2
	s_nop 1
	v_addc_co_u32_e32 v79, vcc, -1, v3, vcc
	global_load_dword v66, v[78:79], off offset:-2048
	global_load_dword v67, v[78:79], off
	v_add_co_u32_e32 v78, vcc, 0xfef0c000, v2
	s_nop 1
	v_addc_co_u32_e32 v79, vcc, -1, v3, vcc
	global_load_dword v68, v[78:79], off offset:-2048
	global_load_dword v69, v[78:79], off
	v_add_co_u32_e32 v78, vcc, 0xfef0d000, v2
	s_nop 1
	v_addc_co_u32_e32 v79, vcc, -1, v3, vcc
	global_load_dword v70, v[78:79], off offset:-2048
	global_load_dword v71, v[78:79], off
	v_add_co_u32_e32 v78, vcc, 0xfef0e000, v2
	s_nop 1
	v_addc_co_u32_e32 v79, vcc, -1, v3, vcc
	global_load_dword v72, v[78:79], off offset:-2048
	global_load_dword v73, v[78:79], off
	v_add_co_u32_e32 v78, vcc, 0xfef0f000, v2
	s_nop 1
	v_addc_co_u32_e32 v79, vcc, -1, v3, vcc
	global_load_dword v74, v[78:79], off offset:-2048
	global_load_dword v75, v[78:79], off
	v_add_co_u32_e32 v78, vcc, 0xfef10000, v2
	s_nop 1
	v_addc_co_u32_e32 v79, vcc, -1, v3, vcc
	global_load_dword v76, v[78:79], off offset:-2048
	global_load_dword v77, v[78:79], off
	v_mov_b32_e32 v18, s4
	s_nop 0
	s_movk_i32 s5, 0xa000
	s_nop 0
	s_add_i32 s1, s1, 16
	s_nop 0
	s_mov_b64 s[6:7], 0x8000
	s_nop 0
	s_add_i32 s4, s4, 64
	s_nop 0
	s_cmpk_gt_u32 s1, 0x6f
	s_nop 0
	s_nop 1
	s_nop 1
	v_add_co_u32_e32 v6, vcc, 0xffff9000, v2
	s_nop 1
	v_addc_co_u32_e32 v7, vcc, -1, v3, vcc
	global_store_dword v[6:7], v4, off offset:-2048
	ds_read_b128 v[22:25], v18
	ds_read_b128 v[26:29], v18 offset:512
	s_waitcnt lgkmcnt(1)
; __device__ __forceinline__ void phase4(const Args& a, LAS unsigned char* lds, int tid, int wave, int lane, int vcu, int G) {
;     ...
;                 for (int c0 = 0; c0 < 128; c0 += 16) { float dn[16];
; #pragma unroll
;                     for (int x = 0; x < 16; ++x) dn[x] = DN[(size_t)((c0 + x) * 4 + hd) * 128 + dk];
; #pragma unroll
;                     for (int x = 0; x < 16; ++x) { NPREV[(size_t)((c0 + x) * 4 + hd) * 128 + dk] = n; n = n * DEC[c0 + x] + dn[x] * SCL[c0 + x]; } }
	v_mov_b32_e32 v30, v22
	s_waitcnt lgkmcnt(0)
	v_mov_b32_e32 v31, v26
	v_mul_f32_e32 v22, v5, v26
	v_pk_fma_f32 v[4:5], v[4:5], v[30:31], v[22:23] op_sel_hi:[1,1,0]
	global_store_dword v[6:7], v4, off
	v_mov_b32_e32 v5, v21
	v_mov_b32_e32 v26, v23
	v_mul_f32_e32 v6, v21, v27
	v_pk_fma_f32 v[4:5], v[4:5], v[26:27], v[6:7] op_sel_hi:[1,1,0]
	v_add_co_u32_e32 v6, vcc, s5, v2
	v_mov_b32_e32 v5, v32
	v_addc_co_u32_e32 v7, vcc, -1, v3, vcc
	global_store_dword v[6:7], v4, off offset:-2048
	v_mov_b32_e32 v6, v24
	v_mov_b32_e32 v7, v28
	v_mul_f32_e32 v22, v32, v28
	s_movk_i32 s5, 0xb000
	v_pk_fma_f32 v[6:7], v[4:5], v[6:7], v[22:23] op_sel_hi:[1,1,0]
	v_add_co_u32_e32 v4, vcc, s5, v2
	v_mov_b32_e32 v7, v33
	v_addc_co_u32_e32 v5, vcc, -1, v3, vcc
	v_mov_b32_e32 v28, v25
	v_mul_f32_e32 v22, v33, v29
	global_store_dword v[4:5], v6, off offset:-4096
	v_pk_fma_f32 v[6:7], v[6:7], v[28:29], v[22:23] op_sel_hi:[1,1,0]
	global_store_dword v[4:5], v6, off offset:-2048
	ds_read_b128 v[22:25], v18 offset:16
	ds_read_b128 v[26:29], v18 offset:528
	v_mov_b32_e32 v7, v20
	s_movk_i32 s5, 0xc000
	s_waitcnt lgkmcnt(1)
	v_mov_b32_e32 v30, v22
	s_waitcnt lgkmcnt(0)
	v_mov_b32_e32 v31, v26
	v_mul_f32_e32 v20, v20, v26
	v_pk_fma_f32 v[6:7], v[6:7], v[30:31], v[20:21] op_sel_hi:[1,1,0]
	global_store_dword v[4:5], v6, off
	v_mov_b32_e32 v7, v19
	v_mov_b32_e32 v26, v23
	v_mul_f32_e32 v4, v19, v27
	v_pk_fma_f32 v[4:5], v[6:7], v[26:27], v[4:5] op_sel_hi:[1,1,0]
	v_add_co_u32_e32 v6, vcc, s5, v2
	v_mov_b32_e32 v5, v17
	v_addc_co_u32_e32 v7, vcc, -1, v3, vcc
	global_store_dword v[6:7], v4, off offset:-2048
	v_mov_b32_e32 v6, v24
	v_mov_b32_e32 v7, v28
	v_mul_f32_e32 v20, v17, v28
	v_pk_fma_f32 v[4:5], v[4:5], v[6:7], v[20:21] op_sel_hi:[1,1,0]
	s_movk_i32 s5, 0xd000
	v_add_co_u32_e32 v26, vcc, s5, v2
	v_mov_b32_e32 v5, v16
	v_mov_b32_e32 v28, v25
	v_mul_f32_e32 v6, v16, v29
	v_addc_co_u32_e32 v27, vcc, -1, v3, vcc
	v_pk_fma_f32 v[16:17], v[4:5], v[28:29], v[6:7] op_sel_hi:[1,1,0]
	global_store_dword v[26:27], v4, off offset:-4096
	global_store_dword v[26:27], v16, off offset:-2048
	ds_read_b128 v[4:7], v18 offset:32
	ds_read_b128 v[20:23], v18 offset:544
	v_mov_b32_e32 v17, v15
	s_movk_i32 s5, 0xe000
	s_waitcnt lgkmcnt(1)
	v_mov_b32_e32 v24, v4
	s_waitcnt lgkmcnt(0)
	v_mov_b32_e32 v25, v20
	v_mul_f32_e32 v4, v15, v20
	v_pk_fma_f32 v[16:17], v[16:17], v[24:25], v[4:5] op_sel_hi:[1,1,0]
	v_mov_b32_e32 v20, v5
	v_mov_b32_e32 v17, v14
	v_mul_f32_e32 v4, v14, v21
	v_pk_fma_f32 v[4:5], v[16:17], v[20:21], v[4:5] op_sel_hi:[1,1,0]
	v_add_co_u32_e32 v14, vcc, s5, v2
	global_store_dword v[26:27], v16, off
	s_nop 0
	v_addc_co_u32_e32 v15, vcc, -1, v3, vcc
	v_mov_b32_e32 v5, v13
	v_mov_b32_e32 v16, v6
	v_mov_b32_e32 v17, v22
	v_mul_f32_e32 v6, v13, v22
	global_store_dword v[14:15], v4, off offset:-2048
	v_pk_fma_f32 v[4:5], v[4:5], v[16:17], v[6:7] op_sel_hi:[1,1,0]
	v_mov_b32_e32 v22, v7
	v_mov_b32_e32 v5, v12
	v_mul_f32_e32 v6, v12, v23
	s_movk_i32 s5, 0xf000
	global_store_dword v[14:15], v4, off
	v_pk_fma_f32 v[16:17], v[4:5], v[22:23], v[6:7] op_sel_hi:[1,1,0]
	v_add_co_u32_e32 v4, vcc, s5, v2
	v_mov_b32_e32 v17, v11
	v_addc_co_u32_e32 v5, vcc, -1, v3, vcc
	global_store_dword v[4:5], v16, off offset:-2048
	ds_read_b128 v[4:7], v18 offset:48
	ds_read_b128 v[12:15], v18 offset:560
	s_waitcnt lgkmcnt(1)
	v_mov_b32_e32 v18, v4
	s_waitcnt lgkmcnt(0)
	v_mov_b32_e32 v19, v12
	v_mul_f32_e32 v4, v11, v12
	v_pk_fma_f32 v[16:17], v[16:17], v[18:19], v[4:5] op_sel_hi:[1,1,0]
	v_mov_b32_e32 v12, v5
	v_mov_b32_e32 v17, v10
	v_mul_f32_e32 v4, v10, v13
	v_pk_fma_f32 v[4:5], v[16:17], v[12:13], v[4:5] op_sel_hi:[1,1,0]
	v_mov_b32_e32 v10, v6
	v_mov_b32_e32 v5, v9
	v_mov_b32_e32 v11, v14
	global_store_dword v[2:3], v4, off offset:-2048
	v_pk_mul_f32 v[4:5], v[4:5], v[10:11]
	global_store_dword v[2:3], v16, off offset:-4096
	v_add_f32_e32 v5, v4, v5
	v_mul_f32_e32 v4, v8, v15
	global_store_dword v[2:3], v5, off
	v_fmac_f32_e32 v4, v5, v7
	v_lshl_add_u64 v[2:3], v[2:3], 0, s[6:7]
	s_waitcnt vmcnt(48)
	v_mov_b32_e32 v5, v46
	v_mov_b32_e32 v21, v47
	v_mov_b32_e32 v32, v48
	v_mov_b32_e32 v33, v49
	v_mov_b32_e32 v20, v50
	v_mov_b32_e32 v19, v51
	v_mov_b32_e32 v17, v52
	v_mov_b32_e32 v16, v53
	v_mov_b32_e32 v15, v54
	v_mov_b32_e32 v14, v55
	v_mov_b32_e32 v13, v56
	v_mov_b32_e32 v12, v57
	v_mov_b32_e32 v11, v58
	v_mov_b32_e32 v10, v59
	v_mov_b32_e32 v9, v60
	v_mov_b32_e32 v8, v61
	v_add_co_u32_e32 v78, vcc, 0xfef09000, v2
	s_nop 1
	v_addc_co_u32_e32 v79, vcc, -1, v3, vcc
	global_load_dword v46, v[78:79], off offset:-2048
	global_load_dword v47, v[78:79], off
	v_add_co_u32_e32 v78, vcc, 0xfef0a000, v2
	s_nop 1
	v_addc_co_u32_e32 v79, vcc, -1, v3, vcc
	global_load_dword v48, v[78:79], off offset:-2048
	global_load_dword v49, v[78:79], off
	v_add_co_u32_e32 v78, vcc, 0xfef0b000, v2
	s_nop 1
	v_addc_co_u32_e32 v79, vcc, -1, v3, vcc
	global_load_dword v50, v[78:79], off offset:-2048
	global_load_dword v51, v[78:79], off
	v_add_co_u32_e32 v78, vcc, 0xfef0c000, v2
	s_nop 1
	v_addc_co_u32_e32 v79, vcc, -1, v3, vcc
	global_load_dword v52, v[78:79], off offset:-2048
	global_load_dword v53, v[78:79], off
	v_add_co_u32_e32 v78, vcc, 0xfef0d000, v2
	s_nop 1
	v_addc_co_u32_e32 v79, vcc, -1, v3, vcc
	global_load_dword v54, v[78:79], off offset:-2048
	global_load_dword v55, v[78:79], off
	v_add_co_u32_e32 v78, vcc, 0xfef0e000, v2
	s_nop 1
	v_addc_co_u32_e32 v79, vcc, -1, v3, vcc
	global_load_dword v56, v[78:79], off offset:-2048
	global_load_dword v57, v[78:79], off
	v_add_co_u32_e32 v78, vcc, 0xfef0f000, v2
	s_nop 1
	v_addc_co_u32_e32 v79, vcc, -1, v3, vcc
	global_load_dword v58, v[78:79], off offset:-2048
	global_load_dword v59, v[78:79], off
	v_add_co_u32_e32 v78, vcc, 0xfef10000, v2
	s_nop 1
	v_addc_co_u32_e32 v79, vcc, -1, v3, vcc
	global_load_dword v60, v[78:79], off offset:-2048
	global_load_dword v61, v[78:79], off
	v_mov_b32_e32 v18, s4
	s_nop 0
	s_movk_i32 s5, 0xa000
	s_nop 0
	s_add_i32 s1, s1, 16
	s_nop 0
	s_mov_b64 s[6:7], 0x8000
	s_nop 0
	s_add_i32 s4, s4, 64
	s_nop 0
	s_cmpk_gt_u32 s1, 0x6f
	s_nop 0
	s_nop 1
	s_nop 1
	v_add_co_u32_e32 v6, vcc, 0xffff9000, v2
	s_nop 1
	v_addc_co_u32_e32 v7, vcc, -1, v3, vcc
	global_store_dword v[6:7], v4, off offset:-2048
	ds_read_b128 v[22:25], v18
	ds_read_b128 v[26:29], v18 offset:512
	s_waitcnt lgkmcnt(1)
; __device__ __forceinline__ void phase4(const Args& a, LAS unsigned char* lds, int tid, int wave, int lane, int vcu, int G) {
;     ...
;                 for (int c0 = 0; c0 < 128; c0 += 16) { float dn[16];
; #pragma unroll
;                     for (int x = 0; x < 16; ++x) dn[x] = DN[(size_t)((c0 + x) * 4 + hd) * 128 + dk];
; #pragma unroll
;                     for (int x = 0; x < 16; ++x) { NPREV[(size_t)((c0 + x) * 4 + hd) * 128 + dk] = n; n = n * DEC[c0 + x] + dn[x] * SCL[c0 + x]; } }
	v_mov_b32_e32 v30, v22
	s_waitcnt lgkmcnt(0)
	v_mov_b32_e32 v31, v26
	v_mul_f32_e32 v22, v5, v26
	v_pk_fma_f32 v[4:5], v[4:5], v[30:31], v[22:23] op_sel_hi:[1,1,0]
	global_store_dword v[6:7], v4, off
	v_mov_b32_e32 v5, v21
	v_mov_b32_e32 v26, v23
	v_mul_f32_e32 v6, v21, v27
	v_pk_fma_f32 v[4:5], v[4:5], v[26:27], v[6:7] op_sel_hi:[1,1,0]
	v_add_co_u32_e32 v6, vcc, s5, v2
	v_mov_b32_e32 v5, v32
	v_addc_co_u32_e32 v7, vcc, -1, v3, vcc
	global_store_dword v[6:7], v4, off offset:-2048
	v_mov_b32_e32 v6, v24
	v_mov_b32_e32 v7, v28
	v_mul_f32_e32 v22, v32, v28
	s_movk_i32 s5, 0xb000
	v_pk_fma_f32 v[6:7], v[4:5], v[6:7], v[22:23] op_sel_hi:[1,1,0]
	v_add_co_u32_e32 v4, vcc, s5, v2
	v_mov_b32_e32 v7, v33
	v_addc_co_u32_e32 v5, vcc, -1, v3, vcc
	v_mov_b32_e32 v28, v25
	v_mul_f32_e32 v22, v33, v29
	global_store_dword v[4:5], v6, off offset:-4096
	v_pk_fma_f32 v[6:7], v[6:7], v[28:29], v[22:23] op_sel_hi:[1,1,0]
	global_store_dword v[4:5], v6, off offset:-2048
	ds_read_b128 v[22:25], v18 offset:16
	ds_read_b128 v[26:29], v18 offset:528
	v_mov_b32_e32 v7, v20
	s_movk_i32 s5, 0xc000
	s_waitcnt lgkmcnt(1)
	v_mov_b32_e32 v30, v22
	s_waitcnt lgkmcnt(0)
	v_mov_b32_e32 v31, v26
	v_mul_f32_e32 v20, v20, v26
	v_pk_fma_f32 v[6:7], v[6:7], v[30:31], v[20:21] op_sel_hi:[1,1,0]
	global_store_dword v[4:5], v6, off
	v_mov_b32_e32 v7, v19
	v_mov_b32_e32 v26, v23
	v_mul_f32_e32 v4, v19, v27
	v_pk_fma_f32 v[4:5], v[6:7], v[26:27], v[4:5] op_sel_hi:[1,1,0]
	v_add_co_u32_e32 v6, vcc, s5, v2
	v_mov_b32_e32 v5, v17
	v_addc_co_u32_e32 v7, vcc, -1, v3, vcc
	global_store_dword v[6:7], v4, off offset:-2048
	v_mov_b32_e32 v6, v24
	v_mov_b32_e32 v7, v28
	v_mul_f32_e32 v20, v17, v28
	v_pk_fma_f32 v[4:5], v[4:5], v[6:7], v[20:21] op_sel_hi:[1,1,0]
	s_movk_i32 s5, 0xd000
	v_add_co_u32_e32 v26, vcc, s5, v2
	v_mov_b32_e32 v5, v16
	v_mov_b32_e32 v28, v25
	v_mul_f32_e32 v6, v16, v29
	v_addc_co_u32_e32 v27, vcc, -1, v3, vcc
	v_pk_fma_f32 v[16:17], v[4:5], v[28:29], v[6:7] op_sel_hi:[1,1,0]
	global_store_dword v[26:27], v4, off offset:-4096
	global_store_dword v[26:27], v16, off offset:-2048
	ds_read_b128 v[4:7], v18 offset:32
	ds_read_b128 v[20:23], v18 offset:544
	v_mov_b32_e32 v17, v15
	s_movk_i32 s5, 0xe000
	s_waitcnt lgkmcnt(1)
	v_mov_b32_e32 v24, v4
	s_waitcnt lgkmcnt(0)
	v_mov_b32_e32 v25, v20
	v_mul_f32_e32 v4, v15, v20
	v_pk_fma_f32 v[16:17], v[16:17], v[24:25], v[4:5] op_sel_hi:[1,1,0]
	v_mov_b32_e32 v20, v5
	v_mov_b32_e32 v17, v14
	v_mul_f32_e32 v4, v14, v21
	v_pk_fma_f32 v[4:5], v[16:17], v[20:21], v[4:5] op_sel_hi:[1,1,0]
	v_add_co_u32_e32 v14, vcc, s5, v2
	global_store_dword v[26:27], v16, off
	s_nop 0
	v_addc_co_u32_e32 v15, vcc, -1, v3, vcc
	v_mov_b32_e32 v5, v13
	v_mov_b32_e32 v16, v6
	v_mov_b32_e32 v17, v22
	v_mul_f32_e32 v6, v13, v22
	global_store_dword v[14:15], v4, off offset:-2048
	v_pk_fma_f32 v[4:5], v[4:5], v[16:17], v[6:7] op_sel_hi:[1,1,0]
	v_mov_b32_e32 v22, v7
	v_mov_b32_e32 v5, v12
	v_mul_f32_e32 v6, v12, v23
	s_movk_i32 s5, 0xf000
	global_store_dword v[14:15], v4, off
	v_pk_fma_f32 v[16:17], v[4:5], v[22:23], v[6:7] op_sel_hi:[1,1,0]
	v_add_co_u32_e32 v4, vcc, s5, v2
	v_mov_b32_e32 v17, v11
	v_addc_co_u32_e32 v5, vcc, -1, v3, vcc
	global_store_dword v[4:5], v16, off offset:-2048
	ds_read_b128 v[4:7], v18 offset:48
	ds_read_b128 v[12:15], v18 offset:560
	s_waitcnt lgkmcnt(1)
	v_mov_b32_e32 v18, v4
	s_waitcnt lgkmcnt(0)
	v_mov_b32_e32 v19, v12
	v_mul_f32_e32 v4, v11, v12
	v_pk_fma_f32 v[16:17], v[16:17], v[18:19], v[4:5] op_sel_hi:[1,1,0]
	v_mov_b32_e32 v12, v5
	v_mov_b32_e32 v17, v10
	v_mul_f32_e32 v4, v10, v13
	v_pk_fma_f32 v[4:5], v[16:17], v[12:13], v[4:5] op_sel_hi:[1,1,0]
	v_mov_b32_e32 v10, v6
	v_mov_b32_e32 v5, v9
	v_mov_b32_e32 v11, v14
	global_store_dword v[2:3], v4, off offset:-2048
	v_pk_mul_f32 v[4:5], v[4:5], v[10:11]
	global_store_dword v[2:3], v16, off offset:-4096
	v_add_f32_e32 v5, v4, v5
	v_mul_f32_e32 v4, v8, v15
	global_store_dword v[2:3], v5, off
	v_fmac_f32_e32 v4, v5, v7
	v_lshl_add_u64 v[2:3], v[2:3], 0, s[6:7]
	s_waitcnt vmcnt(48)
	v_mov_b32_e32 v5, v62
	v_mov_b32_e32 v21, v63
	v_mov_b32_e32 v32, v64
	v_mov_b32_e32 v33, v65
	v_mov_b32_e32 v20, v66
	v_mov_b32_e32 v19, v67
	v_mov_b32_e32 v17, v68
	v_mov_b32_e32 v16, v69
	v_mov_b32_e32 v15, v70
	v_mov_b32_e32 v14, v71
	v_mov_b32_e32 v13, v72
	v_mov_b32_e32 v12, v73
	v_mov_b32_e32 v11, v74
	v_mov_b32_e32 v10, v75
	v_mov_b32_e32 v9, v76
	v_mov_b32_e32 v8, v77
	v_add_co_u32_e32 v78, vcc, 0xfef09000, v2
	s_nop 1
	v_addc_co_u32_e32 v79, vcc, -1, v3, vcc
	global_load_dword v62, v[78:79], off offset:-2048
	global_load_dword v63, v[78:79], off
	v_add_co_u32_e32 v78, vcc, 0xfef0a000, v2
	s_nop 1
	v_addc_co_u32_e32 v79, vcc, -1, v3, vcc
	global_load_dword v64, v[78:79], off offset:-2048
	global_load_dword v65, v[78:79], off
	v_add_co_u32_e32 v78, vcc, 0xfef0b000, v2
	s_nop 1
	v_addc_co_u32_e32 v79, vcc, -1, v3, vcc
	global_load_dword v66, v[78:79], off offset:-2048
	global_load_dword v67, v[78:79], off
	v_add_co_u32_e32 v78, vcc, 0xfef0c000, v2
	s_nop 1
	v_addc_co_u32_e32 v79, vcc, -1, v3, vcc
	global_load_dword v68, v[78:79], off offset:-2048
	global_load_dword v69, v[78:79], off
	v_add_co_u32_e32 v78, vcc, 0xfef0d000, v2
	s_nop 1
	v_addc_co_u32_e32 v79, vcc, -1, v3, vcc
	global_load_dword v70, v[78:79], off offset:-2048
	global_load_dword v71, v[78:79], off
	v_add_co_u32_e32 v78, vcc, 0xfef0e000, v2
	s_nop 1
	v_addc_co_u32_e32 v79, vcc, -1, v3, vcc
	global_load_dword v72, v[78:79], off offset:-2048
	global_load_dword v73, v[78:79], off
	v_add_co_u32_e32 v78, vcc, 0xfef0f000, v2
	s_nop 1
	v_addc_co_u32_e32 v79, vcc, -1, v3, vcc
	global_load_dword v74, v[78:79], off offset:-2048
	global_load_dword v75, v[78:79], off
	v_add_co_u32_e32 v78, vcc, 0xfef10000, v2
	s_nop 1
	v_addc_co_u32_e32 v79, vcc, -1, v3, vcc
	global_load_dword v76, v[78:79], off offset:-2048
	global_load_dword v77, v[78:79], off
	v_mov_b32_e32 v18, s4
	s_nop 0
	s_movk_i32 s5, 0xa000
	s_nop 0
	s_add_i32 s1, s1, 16
	s_nop 0
	s_mov_b64 s[6:7], 0x8000
	s_nop 0
	s_add_i32 s4, s4, 64
	s_nop 0
	s_cmpk_gt_u32 s1, 0x6f
	s_nop 0
	s_nop 1
	s_nop 1
	v_add_co_u32_e32 v6, vcc, 0xffff9000, v2
	s_nop 1
	v_addc_co_u32_e32 v7, vcc, -1, v3, vcc
	global_store_dword v[6:7], v4, off offset:-2048
	ds_read_b128 v[22:25], v18
	ds_read_b128 v[26:29], v18 offset:512
	s_waitcnt lgkmcnt(1)
; __device__ __forceinline__ void phase4(const Args& a, LAS unsigned char* lds, int tid, int wave, int lane, int vcu, int G) {
;     ...
;                 for (int c0 = 0; c0 < 128; c0 += 16) { float dn[16];
; #pragma unroll
;                     for (int x = 0; x < 16; ++x) dn[x] = DN[(size_t)((c0 + x) * 4 + hd) * 128 + dk];
; #pragma unroll
;                     for (int x = 0; x < 16; ++x) { NPREV[(size_t)((c0 + x) * 4 + hd) * 128 + dk] = n; n = n * DEC[c0 + x] + dn[x] * SCL[c0 + x]; } }
	v_mov_b32_e32 v30, v22
	s_waitcnt lgkmcnt(0)
	v_mov_b32_e32 v31, v26
	v_mul_f32_e32 v22, v5, v26
	v_pk_fma_f32 v[4:5], v[4:5], v[30:31], v[22:23] op_sel_hi:[1,1,0]
	global_store_dword v[6:7], v4, off
	v_mov_b32_e32 v5, v21
	v_mov_b32_e32 v26, v23
	v_mul_f32_e32 v6, v21, v27
	v_pk_fma_f32 v[4:5], v[4:5], v[26:27], v[6:7] op_sel_hi:[1,1,0]
	v_add_co_u32_e32 v6, vcc, s5, v2
	v_mov_b32_e32 v5, v32
	v_addc_co_u32_e32 v7, vcc, -1, v3, vcc
	global_store_dword v[6:7], v4, off offset:-2048
	v_mov_b32_e32 v6, v24
	v_mov_b32_e32 v7, v28
	v_mul_f32_e32 v22, v32, v28
	s_movk_i32 s5, 0xb000
	v_pk_fma_f32 v[6:7], v[4:5], v[6:7], v[22:23] op_sel_hi:[1,1,0]
	v_add_co_u32_e32 v4, vcc, s5, v2
	v_mov_b32_e32 v7, v33
	v_addc_co_u32_e32 v5, vcc, -1, v3, vcc
	v_mov_b32_e32 v28, v25
	v_mul_f32_e32 v22, v33, v29
	global_store_dword v[4:5], v6, off offset:-4096
	v_pk_fma_f32 v[6:7], v[6:7], v[28:29], v[22:23] op_sel_hi:[1,1,0]
	global_store_dword v[4:5], v6, off offset:-2048
	ds_read_b128 v[22:25], v18 offset:16
	ds_read_b128 v[26:29], v18 offset:528
	v_mov_b32_e32 v7, v20
	s_movk_i32 s5, 0xc000
	s_waitcnt lgkmcnt(1)
	v_mov_b32_e32 v30, v22
	s_waitcnt lgkmcnt(0)
	v_mov_b32_e32 v31, v26
	v_mul_f32_e32 v20, v20, v26
	v_pk_fma_f32 v[6:7], v[6:7], v[30:31], v[20:21] op_sel_hi:[1,1,0]
	global_store_dword v[4:5], v6, off
	v_mov_b32_e32 v7, v19
	v_mov_b32_e32 v26, v23
	v_mul_f32_e32 v4, v19, v27
	v_pk_fma_f32 v[4:5], v[6:7], v[26:27], v[4:5] op_sel_hi:[1,1,0]
	v_add_co_u32_e32 v6, vcc, s5, v2
	v_mov_b32_e32 v5, v17
	v_addc_co_u32_e32 v7, vcc, -1, v3, vcc
	global_store_dword v[6:7], v4, off offset:-2048
	v_mov_b32_e32 v6, v24
	v_mov_b32_e32 v7, v28
	v_mul_f32_e32 v20, v17, v28
	v_pk_fma_f32 v[4:5], v[4:5], v[6:7], v[20:21] op_sel_hi:[1,1,0]
	s_movk_i32 s5, 0xd000
	v_add_co_u32_e32 v26, vcc, s5, v2
	v_mov_b32_e32 v5, v16
	v_mov_b32_e32 v28, v25
	v_mul_f32_e32 v6, v16, v29
	v_addc_co_u32_e32 v27, vcc, -1, v3, vcc
	v_pk_fma_f32 v[16:17], v[4:5], v[28:29], v[6:7] op_sel_hi:[1,1,0]
	global_store_dword v[26:27], v4, off offset:-4096
	global_store_dword v[26:27], v16, off offset:-2048
	ds_read_b128 v[4:7], v18 offset:32
	ds_read_b128 v[20:23], v18 offset:544
	v_mov_b32_e32 v17, v15
	s_movk_i32 s5, 0xe000
	s_waitcnt lgkmcnt(1)
	v_mov_b32_e32 v24, v4
	s_waitcnt lgkmcnt(0)
	v_mov_b32_e32 v25, v20
	v_mul_f32_e32 v4, v15, v20
	v_pk_fma_f32 v[16:17], v[16:17], v[24:25], v[4:5] op_sel_hi:[1,1,0]
	v_mov_b32_e32 v20, v5
	v_mov_b32_e32 v17, v14
	v_mul_f32_e32 v4, v14, v21
	v_pk_fma_f32 v[4:5], v[16:17], v[20:21], v[4:5] op_sel_hi:[1,1,0]
	v_add_co_u32_e32 v14, vcc, s5, v2
	global_store_dword v[26:27], v16, off
	s_nop 0
	v_addc_co_u32_e32 v15, vcc, -1, v3, vcc
	v_mov_b32_e32 v5, v13
	v_mov_b32_e32 v16, v6
	v_mov_b32_e32 v17, v22
	v_mul_f32_e32 v6, v13, v22
	global_store_dword v[14:15], v4, off offset:-2048
	v_pk_fma_f32 v[4:5], v[4:5], v[16:17], v[6:7] op_sel_hi:[1,1,0]
	v_mov_b32_e32 v22, v7
	v_mov_b32_e32 v5, v12
	v_mul_f32_e32 v6, v12, v23
	s_movk_i32 s5, 0xf000
	global_store_dword v[14:15], v4, off
	v_pk_fma_f32 v[16:17], v[4:5], v[22:23], v[6:7] op_sel_hi:[1,1,0]
	v_add_co_u32_e32 v4, vcc, s5, v2
	v_mov_b32_e32 v17, v11
	v_addc_co_u32_e32 v5, vcc, -1, v3, vcc
	global_store_dword v[4:5], v16, off offset:-2048
	ds_read_b128 v[4:7], v18 offset:48
	ds_read_b128 v[12:15], v18 offset:560
	s_waitcnt lgkmcnt(1)
	v_mov_b32_e32 v18, v4
	s_waitcnt lgkmcnt(0)
	v_mov_b32_e32 v19, v12
	v_mul_f32_e32 v4, v11, v12
	v_pk_fma_f32 v[16:17], v[16:17], v[18:19], v[4:5] op_sel_hi:[1,1,0]
	v_mov_b32_e32 v12, v5
	v_mov_b32_e32 v17, v10
	v_mul_f32_e32 v4, v10, v13
	v_pk_fma_f32 v[4:5], v[16:17], v[12:13], v[4:5] op_sel_hi:[1,1,0]
	v_mov_b32_e32 v10, v6
	v_mov_b32_e32 v5, v9
	v_mov_b32_e32 v11, v14
	global_store_dword v[2:3], v4, off offset:-2048
	v_pk_mul_f32 v[4:5], v[4:5], v[10:11]
	global_store_dword v[2:3], v16, off offset:-4096
	v_add_f32_e32 v5, v4, v5
	v_mul_f32_e32 v4, v8, v15
	global_store_dword v[2:3], v5, off
	v_fmac_f32_e32 v4, v5, v7
	v_lshl_add_u64 v[2:3], v[2:3], 0, s[6:7]
	s_waitcnt vmcnt(48)
	v_mov_b32_e32 v5, v46
	v_mov_b32_e32 v21, v47
	v_mov_b32_e32 v32, v48
	v_mov_b32_e32 v33, v49
	v_mov_b32_e32 v20, v50
	v_mov_b32_e32 v19, v51
	v_mov_b32_e32 v17, v52
	v_mov_b32_e32 v16, v53
	v_mov_b32_e32 v15, v54
	v_mov_b32_e32 v14, v55
	v_mov_b32_e32 v13, v56
	v_mov_b32_e32 v12, v57
	v_mov_b32_e32 v11, v58
	v_mov_b32_e32 v10, v59
	v_mov_b32_e32 v9, v60
	v_mov_b32_e32 v8, v61
	v_mov_b32_e32 v18, s4
	s_nop 0
	s_movk_i32 s5, 0xa000
	s_nop 0
	s_add_i32 s1, s1, 16
	s_nop 0
	s_mov_b64 s[6:7], 0x8000
	s_nop 0
	s_add_i32 s4, s4, 64
	s_nop 0
	s_cmpk_gt_u32 s1, 0x6f
	s_nop 0
	s_nop 1
	s_nop 1
	v_add_co_u32_e32 v6, vcc, 0xffff9000, v2
	s_nop 1
	v_addc_co_u32_e32 v7, vcc, -1, v3, vcc
	global_store_dword v[6:7], v4, off offset:-2048
	ds_read_b128 v[22:25], v18
	ds_read_b128 v[26:29], v18 offset:512
	s_waitcnt lgkmcnt(1)
	v_mov_b32_e32 v30, v22
	s_waitcnt lgkmcnt(0)
	v_mov_b32_e32 v31, v26
	v_mul_f32_e32 v22, v5, v26
	v_pk_fma_f32 v[4:5], v[4:5], v[30:31], v[22:23] op_sel_hi:[1,1,0]
	global_store_dword v[6:7], v4, off
	v_mov_b32_e32 v5, v21
	v_mov_b32_e32 v26, v23
	v_mul_f32_e32 v6, v21, v27
	v_pk_fma_f32 v[4:5], v[4:5], v[26:27], v[6:7] op_sel_hi:[1,1,0]
	v_add_co_u32_e32 v6, vcc, s5, v2
	v_mov_b32_e32 v5, v32
	v_addc_co_u32_e32 v7, vcc, -1, v3, vcc
	global_store_dword v[6:7], v4, off offset:-2048
	v_mov_b32_e32 v6, v24
	v_mov_b32_e32 v7, v28
	v_mul_f32_e32 v22, v32, v28
	s_movk_i32 s5, 0xb000
	v_pk_fma_f32 v[6:7], v[4:5], v[6:7], v[22:23] op_sel_hi:[1,1,0]
	v_add_co_u32_e32 v4, vcc, s5, v2
	v_mov_b32_e32 v7, v33
	v_addc_co_u32_e32 v5, vcc, -1, v3, vcc
	v_mov_b32_e32 v28, v25
	v_mul_f32_e32 v22, v33, v29
	global_store_dword v[4:5], v6, off offset:-4096
	v_pk_fma_f32 v[6:7], v[6:7], v[28:29], v[22:23] op_sel_hi:[1,1,0]
	global_store_dword v[4:5], v6, off offset:-2048
	ds_read_b128 v[22:25], v18 offset:16
	ds_read_b128 v[26:29], v18 offset:528
	v_mov_b32_e32 v7, v20
	s_movk_i32 s5, 0xc000
	s_waitcnt lgkmcnt(1)
; __device__ __forceinline__ void phase4(const Args& a, LAS unsigned char* lds, int tid, int wave, int lane, int vcu, int G) {
;     ...
;                 for (int c0 = 0; c0 < 128; c0 += 16) { float dn[16];
; #pragma unroll
;                     for (int x = 0; x < 16; ++x) dn[x] = DN[(size_t)((c0 + x) * 4 + hd) * 128 + dk];
; #pragma unroll
;                     for (int x = 0; x < 16; ++x) { NPREV[(size_t)((c0 + x) * 4 + hd) * 128 + dk] = n; n = n * DEC[c0 + x] + dn[x] * SCL[c0 + x]; } }
	v_mov_b32_e32 v30, v22
	s_waitcnt lgkmcnt(0)
	v_mov_b32_e32 v31, v26
	v_mul_f32_e32 v20, v20, v26
	v_pk_fma_f32 v[6:7], v[6:7], v[30:31], v[20:21] op_sel_hi:[1,1,0]
	global_store_dword v[4:5], v6, off
	v_mov_b32_e32 v7, v19
	v_mov_b32_e32 v26, v23
	v_mul_f32_e32 v4, v19, v27
	v_pk_fma_f32 v[4:5], v[6:7], v[26:27], v[4:5] op_sel_hi:[1,1,0]
	v_add_co_u32_e32 v6, vcc, s5, v2
	v_mov_b32_e32 v5, v17
	v_addc_co_u32_e32 v7, vcc, -1, v3, vcc
	global_store_dword v[6:7], v4, off offset:-2048
	v_mov_b32_e32 v6, v24
	v_mov_b32_e32 v7, v28
	v_mul_f32_e32 v20, v17, v28
	v_pk_fma_f32 v[4:5], v[4:5], v[6:7], v[20:21] op_sel_hi:[1,1,0]
	s_movk_i32 s5, 0xd000
	v_add_co_u32_e32 v26, vcc, s5, v2
	v_mov_b32_e32 v5, v16
	v_mov_b32_e32 v28, v25
	v_mul_f32_e32 v6, v16, v29
	v_addc_co_u32_e32 v27, vcc, -1, v3, vcc
	v_pk_fma_f32 v[16:17], v[4:5], v[28:29], v[6:7] op_sel_hi:[1,1,0]
	global_store_dword v[26:27], v4, off offset:-4096
	global_store_dword v[26:27], v16, off offset:-2048
	ds_read_b128 v[4:7], v18 offset:32
	ds_read_b128 v[20:23], v18 offset:544
	v_mov_b32_e32 v17, v15
	s_movk_i32 s5, 0xe000
	s_waitcnt lgkmcnt(1)
	v_mov_b32_e32 v24, v4
	s_waitcnt lgkmcnt(0)
	v_mov_b32_e32 v25, v20
	v_mul_f32_e32 v4, v15, v20
	v_pk_fma_f32 v[16:17], v[16:17], v[24:25], v[4:5] op_sel_hi:[1,1,0]
	v_mov_b32_e32 v20, v5
	v_mov_b32_e32 v17, v14
	v_mul_f32_e32 v4, v14, v21
	v_pk_fma_f32 v[4:5], v[16:17], v[20:21], v[4:5] op_sel_hi:[1,1,0]
	v_add_co_u32_e32 v14, vcc, s5, v2
	global_store_dword v[26:27], v16, off
	s_nop 0
	v_addc_co_u32_e32 v15, vcc, -1, v3, vcc
	v_mov_b32_e32 v5, v13
	v_mov_b32_e32 v16, v6
	v_mov_b32_e32 v17, v22
	v_mul_f32_e32 v6, v13, v22
	global_store_dword v[14:15], v4, off offset:-2048
	v_pk_fma_f32 v[4:5], v[4:5], v[16:17], v[6:7] op_sel_hi:[1,1,0]
	v_mov_b32_e32 v22, v7
	v_mov_b32_e32 v5, v12
	v_mul_f32_e32 v6, v12, v23
	s_movk_i32 s5, 0xf000
	global_store_dword v[14:15], v4, off
	v_pk_fma_f32 v[16:17], v[4:5], v[22:23], v[6:7] op_sel_hi:[1,1,0]
	v_add_co_u32_e32 v4, vcc, s5, v2
	v_mov_b32_e32 v17, v11
	v_addc_co_u32_e32 v5, vcc, -1, v3, vcc
	global_store_dword v[4:5], v16, off offset:-2048
	ds_read_b128 v[4:7], v18 offset:48
	ds_read_b128 v[12:15], v18 offset:560
	s_waitcnt lgkmcnt(1)
	v_mov_b32_e32 v18, v4
	s_waitcnt lgkmcnt(0)
	v_mov_b32_e32 v19, v12
	v_mul_f32_e32 v4, v11, v12
	v_pk_fma_f32 v[16:17], v[16:17], v[18:19], v[4:5] op_sel_hi:[1,1,0]
	v_mov_b32_e32 v12, v5
	v_mov_b32_e32 v17, v10
	v_mul_f32_e32 v4, v10, v13
	v_pk_fma_f32 v[4:5], v[16:17], v[12:13], v[4:5] op_sel_hi:[1,1,0]
	v_mov_b32_e32 v10, v6
	v_mov_b32_e32 v5, v9
	v_mov_b32_e32 v11, v14
	global_store_dword v[2:3], v4, off offset:-2048
	v_pk_mul_f32 v[4:5], v[4:5], v[10:11]
	global_store_dword v[2:3], v16, off offset:-4096
	v_add_f32_e32 v5, v4, v5
	v_mul_f32_e32 v4, v8, v15
	global_store_dword v[2:3], v5, off
	v_fmac_f32_e32 v4, v5, v7
	v_lshl_add_u64 v[2:3], v[2:3], 0, s[6:7]
	s_waitcnt vmcnt(32)
	v_mov_b32_e32 v5, v62
	v_mov_b32_e32 v21, v63
	v_mov_b32_e32 v32, v64
	v_mov_b32_e32 v33, v65
	v_mov_b32_e32 v20, v66
	v_mov_b32_e32 v19, v67
	v_mov_b32_e32 v17, v68
	v_mov_b32_e32 v16, v69
	v_mov_b32_e32 v15, v70
	v_mov_b32_e32 v14, v71
	v_mov_b32_e32 v13, v72
	v_mov_b32_e32 v12, v73
	v_mov_b32_e32 v11, v74
	v_mov_b32_e32 v10, v75
	v_mov_b32_e32 v9, v76
	v_mov_b32_e32 v8, v77
	v_mov_b32_e32 v18, s4
	s_nop 0
	s_movk_i32 s5, 0xa000
	s_nop 0
	s_add_i32 s1, s1, 16
	s_nop 0
	s_mov_b64 s[6:7], 0x8000
	s_nop 0
	s_add_i32 s4, s4, 64
	s_nop 0
	s_cmpk_gt_u32 s1, 0x6f
	s_nop 0
	s_nop 1
	s_nop 1
	v_add_co_u32_e32 v6, vcc, 0xffff9000, v2
	s_nop 1
	v_addc_co_u32_e32 v7, vcc, -1, v3, vcc
	global_store_dword v[6:7], v4, off offset:-2048
	ds_read_b128 v[22:25], v18
	ds_read_b128 v[26:29], v18 offset:512
	s_waitcnt lgkmcnt(1)
	v_mov_b32_e32 v30, v22
	s_waitcnt lgkmcnt(0)
; __device__ __forceinline__ void phase4(const Args& a, LAS unsigned char* lds, int tid, int wave, int lane, int vcu, int G) {
;     ...
;                 for (int c0 = 0; c0 < 128; c0 += 16) { float dn[16];
; #pragma unroll
;                     for (int x = 0; x < 16; ++x) dn[x] = DN[(size_t)((c0 + x) * 4 + hd) * 128 + dk];
; #pragma unroll
;                     for (int x = 0; x < 16; ++x) { NPREV[(size_t)((c0 + x) * 4 + hd) * 128 + dk] = n; n = n * DEC[c0 + x] + dn[x] * SCL[c0 + x]; } }
;                 a.out[O_NP + hd * 128 + dk] = n;
	v_mov_b32_e32 v31, v26
	v_mul_f32_e32 v22, v5, v26
	v_pk_fma_f32 v[4:5], v[4:5], v[30:31], v[22:23] op_sel_hi:[1,1,0]
	global_store_dword v[6:7], v4, off
	v_mov_b32_e32 v5, v21
	v_mov_b32_e32 v26, v23
	v_mul_f32_e32 v6, v21, v27
	v_pk_fma_f32 v[4:5], v[4:5], v[26:27], v[6:7] op_sel_hi:[1,1,0]
	v_add_co_u32_e32 v6, vcc, s5, v2
	v_mov_b32_e32 v5, v32
	v_addc_co_u32_e32 v7, vcc, -1, v3, vcc
	global_store_dword v[6:7], v4, off offset:-2048
	v_mov_b32_e32 v6, v24
	v_mov_b32_e32 v7, v28
	v_mul_f32_e32 v22, v32, v28
	s_movk_i32 s5, 0xb000
	v_pk_fma_f32 v[6:7], v[4:5], v[6:7], v[22:23] op_sel_hi:[1,1,0]
	v_add_co_u32_e32 v4, vcc, s5, v2
	v_mov_b32_e32 v7, v33
	v_addc_co_u32_e32 v5, vcc, -1, v3, vcc
	v_mov_b32_e32 v28, v25
	v_mul_f32_e32 v22, v33, v29
	global_store_dword v[4:5], v6, off offset:-4096
	v_pk_fma_f32 v[6:7], v[6:7], v[28:29], v[22:23] op_sel_hi:[1,1,0]
	global_store_dword v[4:5], v6, off offset:-2048
	ds_read_b128 v[22:25], v18 offset:16
	ds_read_b128 v[26:29], v18 offset:528
	v_mov_b32_e32 v7, v20
	s_movk_i32 s5, 0xc000
	s_waitcnt lgkmcnt(1)
	v_mov_b32_e32 v30, v22
	s_waitcnt lgkmcnt(0)
	v_mov_b32_e32 v31, v26
	v_mul_f32_e32 v20, v20, v26
	v_pk_fma_f32 v[6:7], v[6:7], v[30:31], v[20:21] op_sel_hi:[1,1,0]
	global_store_dword v[4:5], v6, off
	v_mov_b32_e32 v7, v19
	v_mov_b32_e32 v26, v23
	v_mul_f32_e32 v4, v19, v27
	v_pk_fma_f32 v[4:5], v[6:7], v[26:27], v[4:5] op_sel_hi:[1,1,0]
	v_add_co_u32_e32 v6, vcc, s5, v2
	v_mov_b32_e32 v5, v17
	v_addc_co_u32_e32 v7, vcc, -1, v3, vcc
	global_store_dword v[6:7], v4, off offset:-2048
	v_mov_b32_e32 v6, v24
	v_mov_b32_e32 v7, v28
	v_mul_f32_e32 v20, v17, v28
	v_pk_fma_f32 v[4:5], v[4:5], v[6:7], v[20:21] op_sel_hi:[1,1,0]
	s_movk_i32 s5, 0xd000
	v_add_co_u32_e32 v26, vcc, s5, v2
	v_mov_b32_e32 v5, v16
	v_mov_b32_e32 v28, v25
	v_mul_f32_e32 v6, v16, v29
	v_addc_co_u32_e32 v27, vcc, -1, v3, vcc
	v_pk_fma_f32 v[16:17], v[4:5], v[28:29], v[6:7] op_sel_hi:[1,1,0]
	global_store_dword v[26:27], v4, off offset:-4096
	global_store_dword v[26:27], v16, off offset:-2048
	ds_read_b128 v[4:7], v18 offset:32
	ds_read_b128 v[20:23], v18 offset:544
	v_mov_b32_e32 v17, v15
	s_movk_i32 s5, 0xe000
	s_waitcnt lgkmcnt(1)
	v_mov_b32_e32 v24, v4
	s_waitcnt lgkmcnt(0)
	v_mov_b32_e32 v25, v20
	v_mul_f32_e32 v4, v15, v20
	v_pk_fma_f32 v[16:17], v[16:17], v[24:25], v[4:5] op_sel_hi:[1,1,0]
	v_mov_b32_e32 v20, v5
	v_mov_b32_e32 v17, v14
	v_mul_f32_e32 v4, v14, v21
	v_pk_fma_f32 v[4:5], v[16:17], v[20:21], v[4:5] op_sel_hi:[1,1,0]
	v_add_co_u32_e32 v14, vcc, s5, v2
	global_store_dword v[26:27], v16, off
	s_nop 0
	v_addc_co_u32_e32 v15, vcc, -1, v3, vcc
	v_mov_b32_e32 v5, v13
	v_mov_b32_e32 v16, v6
	v_mov_b32_e32 v17, v22
	v_mul_f32_e32 v6, v13, v22
	global_store_dword v[14:15], v4, off offset:-2048
	v_pk_fma_f32 v[4:5], v[4:5], v[16:17], v[6:7] op_sel_hi:[1,1,0]
	v_mov_b32_e32 v22, v7
	v_mov_b32_e32 v5, v12
	v_mul_f32_e32 v6, v12, v23
	s_movk_i32 s5, 0xf000
	global_store_dword v[14:15], v4, off
	v_pk_fma_f32 v[16:17], v[4:5], v[22:23], v[6:7] op_sel_hi:[1,1,0]
	v_add_co_u32_e32 v4, vcc, s5, v2
	v_mov_b32_e32 v17, v11
	v_addc_co_u32_e32 v5, vcc, -1, v3, vcc
	global_store_dword v[4:5], v16, off offset:-2048
	ds_read_b128 v[4:7], v18 offset:48
	ds_read_b128 v[12:15], v18 offset:560
	s_waitcnt lgkmcnt(1)
	v_mov_b32_e32 v18, v4
	s_waitcnt lgkmcnt(0)
	v_mov_b32_e32 v19, v12
	v_mul_f32_e32 v4, v11, v12
	v_pk_fma_f32 v[16:17], v[16:17], v[18:19], v[4:5] op_sel_hi:[1,1,0]
	v_mov_b32_e32 v12, v5
	v_mov_b32_e32 v17, v10
	v_mul_f32_e32 v4, v10, v13
	v_pk_fma_f32 v[4:5], v[16:17], v[12:13], v[4:5] op_sel_hi:[1,1,0]
	v_mov_b32_e32 v10, v6
	v_mov_b32_e32 v5, v9
	v_mov_b32_e32 v11, v14
	global_store_dword v[2:3], v4, off offset:-2048
	v_pk_mul_f32 v[4:5], v[4:5], v[10:11]
	global_store_dword v[2:3], v16, off offset:-4096
	v_add_f32_e32 v5, v4, v5
	v_mul_f32_e32 v4, v8, v15
	global_store_dword v[2:3], v5, off
	v_fmac_f32_e32 v4, v5, v7
	v_lshl_add_u64 v[2:3], v[2:3], 0, s[6:7]
	s_lshl_b32 s0, s0, 7
	s_ashr_i32 s1, s0, 31
	v_readlane_b32 s4, v253, 33
	s_lshl_b64 s[0:1], s[0:1], 2
	v_readlane_b32 s18, v253, 47
	v_readlane_b32 s19, v253, 48
	s_add_u32 s0, s18, s0
	s_addc_u32 s1, s19, s1
	v_mov_b32_e32 v131, v117
	v_lshl_add_u64 v[2:3], s[0:1], 0, v[130:131]
	v_add_co_u32_e32 v2, vcc, 0x5040000, v2
	v_readlane_b32 s5, v253, 34
	s_nop 0
	v_addc_co_u32_e32 v3, vcc, 0, v3, vcc
	v_readlane_b32 s6, v253, 35
	v_readlane_b32 s7, v253, 36
	v_readlane_b32 s8, v253, 37
	v_readlane_b32 s9, v253, 38
	v_readlane_b32 s10, v253, 39
	v_readlane_b32 s11, v253, 40
	v_readlane_b32 s12, v253, 41
	v_readlane_b32 s13, v253, 42
	v_readlane_b32 s14, v253, 43
	v_readlane_b32 s15, v253, 44
	v_readlane_b32 s16, v253, 45
	v_readlane_b32 s17, v253, 46
	global_store_dword v[2:3], v4, off
	s_branch .LBB0_967
